# counted lgkmcnt: FoX QK^T K-fragment LDS reads pipelined 3 deep as well
# baseline (speedup 1.0000x reference)
; #define LAS __attribute__((address_space(3)))
; #define MFMA32(a, b, c) __builtin_amdgcn_mfma_f32_32x32x16_bf16((a), (b), (c), 0, 0, 0)
; template <int MODE> DI void attn_h1(AttnCtx& c, const bf16x8 (&q)[8], f32x16 (&o)[4], f32x16& s0, f32x16& s1, ldsp lds, int kbuf, int bbuf, int tj, int lane) {
;     ...
;             ldsp kl = lds + kbuf + r32 * KPITCH + h * 16;
; #pragma unroll
;             for (int e = 0; e < 16; ++e) { s0[e] = 0.f; s1[e] = 0.f; }
; #pragma unroll
;             for (int s = 0; s < 8; ++s) {
;                 const bf16x8 ka = *(const LAS bf16x8*)(kl + s * 32), kb = *(const LAS bf16x8*)(kl + 32 * KPITCH + s * 32);
;                 s0 = MFMA32(ka, q[s], s0); s1 = MFMA32(kb, q[s], s1);
;                 if (s == 3) asm volatile("" ::: "memory");
;             }
;             const float NINF = -__builtin_inff();
;             if (MODE == MD_FOX) {
;                 const LAS float* bl = (const LAS float*)(lds + A_BIAS + bbuf);
;                 const int kbase = tj * 64 + 4 * h;
;                 const bool needmask = tj >= c.whi;
; #pragma unroll
;                 for (int g4 = 0; g4 < 4; ++g4) {
;                     const f32x4 b0 = *(const LAS f32x4*)(bl + 8 * g4 + 4 * h), b1 = *(const LAS f32x4*)(bl + 32 + 8 * g4 + 4 * h);
; #pragma unroll
;                     for (int e = 0; e < 4; ++e) { s0[4 * g4 + e] += b0[e]; s1[4 * g4 + e] += b1[e]; }
;                 }
.LBB0_564:
	s_or_b64 exec, exec, s[4:5]
	v_cmp_le_i32_e32 vcc, s95, v242
	s_and_b32 s21, s96, 1
	s_and_b64 s[22:23], vcc, s[2:3]
	s_and_saveexec_b64 s[24:25], s[22:23]
	s_cbranch_execz .LBB0_569
	s_mul_i32 s2, s21, 0x4400
	v_add_u32_e32 v0, s2, v237
	ds_read_b128 v[98:101], v0 offset:8704
	ds_read_b128 v[82:85], v0
	ds_read_b128 v[178:181], v0 offset:32
	ds_read_b128 v[182:185], v0 offset:8736
	ds_read_b128 v[206:209], v0 offset:64
	ds_read_b128 v[210:213], v0 offset:8768
	ds_read_b128 v[214:217], v0 offset:96
	ds_read_b128 v[218:221], v0 offset:8800
	v_cmp_ge_i32_e32 vcc, s95, v242
	s_waitcnt lgkmcnt(6)
	v_mfma_f32_32x32x16_bf16 v[98:113], v[98:101], v[136:139], 0
	v_mfma_f32_32x32x16_bf16 v[82:97], v[82:85], v[136:139], 0
	s_waitcnt lgkmcnt(4)
	v_mfma_f32_32x32x16_bf16 v[82:97], v[178:181], v[140:143], v[82:97]
	v_mfma_f32_32x32x16_bf16 v[98:113], v[182:185], v[140:143], v[98:113]
	ds_read_b128 v[178:181], v0 offset:128
	ds_read_b128 v[182:185], v0 offset:8832
	s_waitcnt lgkmcnt(4)
	v_mfma_f32_32x32x16_bf16 v[82:97], v[206:209], v[144:147], v[82:97]
	v_mfma_f32_32x32x16_bf16 v[98:113], v[210:213], v[144:147], v[98:113]
	ds_read_b128 v[206:209], v0 offset:160
	ds_read_b128 v[210:213], v0 offset:8864
	s_waitcnt lgkmcnt(4)
	v_mfma_f32_32x32x16_bf16 v[82:97], v[214:217], v[148:151], v[82:97]
	v_mfma_f32_32x32x16_bf16 v[98:113], v[218:221], v[148:151], v[98:113]
	ds_read_b128 v[214:217], v0 offset:192
	ds_read_b128 v[218:221], v0 offset:8896
	s_waitcnt lgkmcnt(4)
	v_mfma_f32_32x32x16_bf16 v[82:97], v[178:181], v[152:155], v[82:97]
	v_mfma_f32_32x32x16_bf16 v[98:113], v[182:185], v[152:155], v[98:113]
	ds_read_b128 v[178:181], v0 offset:224
	ds_read_b128 v[182:185], v0 offset:8928
	v_lshl_add_u32 v0, s21, 8, v243
	s_waitcnt lgkmcnt(4)
	v_mfma_f32_32x32x16_bf16 v[82:97], v[206:209], v[156:159], v[82:97]
	v_mfma_f32_32x32x16_bf16 v[98:113], v[210:213], v[156:159], v[98:113]
	s_waitcnt lgkmcnt(2)
	v_mfma_f32_32x32x16_bf16 v[82:97], v[214:217], v[160:163], v[82:97]
	v_mfma_f32_32x32x16_bf16 v[98:113], v[218:221], v[160:163], v[98:113]
	s_waitcnt lgkmcnt(0)
	v_mfma_f32_32x32x16_bf16 v[82:97], v[178:181], v[164:167], v[82:97]
	v_mfma_f32_32x32x16_bf16 v[98:113], v[182:185], v[164:167], v[98:113]
	ds_read_b128 v[178:181], v0
	ds_read_b128 v[182:185], v0 offset:32
	ds_read_b128 v[202:205], v0 offset:128
	s_waitcnt lgkmcnt(2)
	s_nop 6
	v_add_f32_e64 v82, v82, v178
	v_add_f32_e64 v83, v83, v179
	v_add_f32_e64 v84, v84, v180
	v_add_f32_e64 v85, v85, v181
	ds_read_b128 v[178:181], v0 offset:160
	s_waitcnt lgkmcnt(2)
	v_add_f32_e64 v86, v86, v182
	v_add_f32_e64 v87, v87, v183
	v_add_f32_e64 v88, v88, v184
	v_add_f32_e64 v89, v89, v185
	s_waitcnt lgkmcnt(1)
	v_add_f32_e64 v98, v98, v202
	v_add_f32_e64 v99, v99, v203
	v_add_f32_e64 v100, v100, v204
	v_add_f32_e64 v101, v101, v205
	s_waitcnt lgkmcnt(0)
	v_add_f32_e64 v102, v102, v178
	v_add_f32_e64 v103, v103, v179
	v_add_f32_e64 v104, v104, v180
	v_add_f32_e64 v105, v105, v181
	ds_read_b128 v[178:181], v0 offset:64
	ds_read_b128 v[182:185], v0 offset:192
	s_waitcnt lgkmcnt(1)
	v_add_f32_e64 v90, v90, v178
	v_add_f32_e64 v91, v91, v179
	s_waitcnt lgkmcnt(0)
	v_add_f32_e64 v106, v106, v182
	v_add_f32_e64 v107, v107, v183
	v_add_f32_e64 v92, v92, v180
	v_add_f32_e64 v93, v93, v181
	v_add_f32_e64 v108, v108, v184
	v_add_f32_e64 v109, v109, v185
	ds_read_b128 v[178:181], v0 offset:96
	ds_read_b128 v[182:185], v0 offset:224
	s_waitcnt lgkmcnt(1)
	v_add_f32_e64 v94, v94, v178
	v_add_f32_e64 v95, v95, v179
	s_waitcnt lgkmcnt(0)
	v_add_f32_e64 v110, v110, v182
	v_add_f32_e64 v111, v111, v183
	v_add_f32_e64 v96, v96, v180
	v_add_f32_e64 v97, v97, v181
	v_add_f32_e64 v112, v112, v184
	v_add_f32_e64 v113, v113, v185
	s_and_saveexec_b64 s[26:27], vcc
	s_cbranch_execz .LBB0_567
; template <int MODE> DI void attn_h1(AttnCtx& c, const bf16x8 (&q)[8], f32x16 (&o)[4], f32x16& s0, f32x16& s1, ldsp lds, int kbuf, int bbuf, int tj, int lane) {
;     ...
;                 if (needmask) {
; #pragma unroll
;                     for (int e = 0; e < 16; ++e) {
;                         const int k0 = kbase + 8 * (e >> 2) + (e & 3);
;                         s0[e] = (k0 <= c.t) ? s0[e] : NINF; s1[e] = (k0 + 32 <= c.t) ? s1[e] : NINF;
;                     }
;                 }
	v_or_b32_e32 v0, 3, v244
	v_cmp_le_i32_e32 vcc, v0, v115
	v_or_b32_e32 v0, 2, v244
	v_cmp_le_i32_e64 s[2:3], v0, v196
	v_or_b32_e32 v0, 9, v244
	v_cmp_le_i32_e64 s[4:5], v0, v115
	v_or_b32_e32 v0, 8, v244
	v_cmp_le_i32_e64 s[6:7], v0, v196
	v_or_b32_e32 v0, 11, v244
	v_cmp_le_i32_e64 s[8:9], v0, v115
	v_or_b32_e32 v0, 10, v244
	v_cmp_le_i32_e64 s[10:11], v0, v196
	v_or_b32_e32 v0, 17, v244
	v_cmp_le_i32_e64 s[12:13], v0, v115
	v_or_b32_e32 v0, 16, v244
	v_cmp_le_i32_e64 s[14:15], v0, v196
	v_or_b32_e32 v0, 19, v244
	v_cmp_le_i32_e64 s[48:49], v0, v115
	v_or_b32_e32 v0, 18, v244
	v_cmp_le_i32_e64 s[50:51], v0, v196
	v_or_b32_e32 v0, 25, v244
	v_cmp_le_i32_e64 s[52:53], v0, v115
	v_or_b32_e32 v0, 24, v244
	v_cmp_le_i32_e64 s[54:55], v0, v196
	v_or_b32_e32 v0, 27, v244
	v_cmp_le_i32_e64 s[56:57], v0, v115
	v_or_b32_e32 v0, 26, v244
	v_cmp_le_i32_e64 s[58:59], v0, v196
	v_or_b32_e32 v0, 59, v244
	v_cmp_le_i32_e64 s[60:61], v0, v33
	v_or_b32_e32 v0, 58, v244
	v_cmp_le_i32_e64 s[62:63], v0, v114
	v_or_b32_e32 v0, 57, v244
	v_cmp_le_i32_e64 s[64:65], v0, v15
	v_or_b32_e32 v0, 56, v244
	v_cmp_le_i32_e64 s[66:67], v0, v14
	v_or_b32_e32 v0, 51, v244
	v_cmp_le_i32_e64 s[68:69], v0, v13
	v_or_b32_e32 v0, 50, v244
	v_cmp_le_i32_e64 s[70:71], v0, v12
	v_or_b32_e32 v0, 49, v244
	v_cmp_le_i32_e64 s[72:73], v0, v11
	v_or_b32_e32 v0, 48, v244
	v_cmp_le_i32_e64 s[74:75], v0, v10
	v_or_b32_e32 v0, 43, v244
	v_cmp_le_i32_e64 s[76:77], v0, v9
	v_or_b32_e32 v0, 42, v244
	v_cmp_le_i32_e64 s[78:79], v0, v8
	v_or_b32_e32 v0, 41, v244
	v_cmp_le_i32_e64 s[80:81], v0, v7
	v_or_b32_e32 v0, 40, v244
	v_cmp_le_i32_e64 s[82:83], v0, v6
	v_or_b32_e32 v0, 35, v244
	v_cmp_le_i32_e64 s[84:85], v0, v5
	v_or_b32_e32 v0, 34, v244
	v_cmp_le_i32_e64 s[86:87], v0, v4
	v_or_b32_e32 v0, 33, v244
	v_cmp_le_i32_e64 s[88:89], v0, v3
	v_or_b32_e32 v0, 32, v244
	v_cmp_le_i32_e64 s[92:93], v244, v196
	v_cmp_le_i32_e64 s[90:91], v0, v2
	v_cndmask_b32_e64 v103, v230, v103, s[80:81]
	v_cndmask_b32_e64 v82, v230, v82, s[92:93]
	v_cmp_lt_i32_e64 s[92:93], v244, v196
	v_readlane_b32 s80, v254, 38
	v_cndmask_b32_e32 v85, v230, v85, vcc
	v_cndmask_b32_e64 v83, v230, v83, s[92:93]
	v_cndmask_b32_e64 v84, v230, v84, s[2:3]
	v_cndmask_b32_e64 v87, v230, v87, s[4:5]
	v_cndmask_b32_e64 v86, v230, v86, s[6:7]
	v_cndmask_b32_e64 v89, v230, v89, s[8:9]
	v_cndmask_b32_e64 v88, v230, v88, s[10:11]
	v_cndmask_b32_e64 v91, v230, v91, s[12:13]
	v_cndmask_b32_e64 v90, v230, v90, s[14:15]
	v_cndmask_b32_e64 v93, v230, v93, s[48:49]
	v_cndmask_b32_e64 v92, v230, v92, s[50:51]
	v_cndmask_b32_e64 v95, v230, v95, s[52:53]
	s_mov_b32 s53, 0xff800000
	s_mov_b32 s52, 0x800000
	v_cndmask_b32_e64 v94, v230, v94, s[54:55]
	v_cndmask_b32_e64 v97, v230, v97, s[56:57]
	v_cndmask_b32_e64 v96, v230, v96, s[58:59]
	v_cndmask_b32_e64 v113, v230, v113, s[60:61]
	v_cndmask_b32_e64 v112, v230, v112, s[62:63]
	v_cndmask_b32_e64 v111, v230, v111, s[64:65]
	v_cndmask_b32_e64 v110, v230, v110, s[66:67]
	v_cndmask_b32_e64 v109, v230, v109, s[68:69]
	v_cndmask_b32_e64 v108, v230, v108, s[70:71]
	v_cndmask_b32_e64 v107, v230, v107, s[72:73]
	v_cndmask_b32_e64 v106, v230, v106, s[74:75]
	v_cndmask_b32_e64 v105, v230, v105, s[76:77]
	v_cndmask_b32_e64 v104, v230, v104, s[78:79]
	v_cndmask_b32_e64 v102, v230, v102, s[82:83]
	v_cndmask_b32_e64 v101, v230, v101, s[84:85]
	v_cndmask_b32_e64 v100, v230, v100, s[86:87]
	v_cndmask_b32_e64 v99, v230, v99, s[88:89]
	v_readlane_b32 s81, v254, 39
	v_cndmask_b32_e64 v98, v230, v98, s[90:91]
